# static priority raise for the older wave half (waves 0-3) before every 8-wave GEMM loop, per-MFMA-block s_setprio flips deleted
# speedup vs baseline: 1.0121x; 1.0114x over previous
.LBB0_821:
	v_lshrrev_b32_e32 v3, 1, v10
	v_lshrrev_b32_e32 v4, 5, v10
	v_and_b32_e32 v3, 24, v3
	v_and_b32_e32 v4, 4, v4
	v_bfe_u32 v5, v10, 2, 2
	s_ashr_i32 s0, s7, 3
	v_lshlrev_b32_e32 v1, 4, v10
	v_and_b32_e32 v2, 32, v10
	v_bfe_u32 v13, v10, 2, 4
	v_or3_b32 v3, v4, v5, v3
	v_lshrrev_b32_e32 v4, 3, v10
	s_movk_i32 s7, 0x70
	v_bitop3_b32 v11, v1, v2, 48 bitop3:0x6c
	v_and_b32_e32 v12, 64, v10
	v_and_or_b32 v5, v4, s7, v13
	s_movk_i32 s7, 0x60
	v_add_u32_e32 v14, 0x2000, v1
	v_or_b32_e32 v2, v11, v12
	v_and_or_b32 v4, v4, s7, v3
	v_lshrrev_b32_e32 v1, 7, v14
	s_movk_i32 s7, 0xf0
	s_add_i32 s0, s6, s0
	v_lshl_or_b32 v132, v4, 11, v2
	v_and_or_b32 v4, v1, s7, v13
	s_movk_i32 s7, 0xe0
	s_mul_hi_i32 s6, s0, 0x2e8ba2e9
	v_and_or_b32 v1, v1, s7, v3
	s_lshr_b32 s7, s6, 31
	s_ashr_i32 s6, s6, 5
	s_add_i32 s6, s6, s7
	s_lshl_b32 s8, s6, 3
	s_sub_i32 s7, 0x45, s8
	s_mulk_i32 s6, 0xb0
	s_min_u32 s9, s7, 8
	s_sub_i32 s11, s0, s6
	v_lshl_or_b32 v130, v5, 11, v2
	v_lshl_or_b32 v134, v4, 11, v2
	v_lshl_or_b32 v136, v1, 11, v2
	s_sext_i32_i16 s0, s11
	v_cvt_f32_ubyte0_e32 v2, s9
	v_cvt_f32_i32_e32 v1, s0
	v_rcp_iflag_f32_e32 v3, v2
	s_lshr_b32 s10, s12, 6
	s_ashr_i32 s0, s0, 30
	s_lshr_b32 s1, s12, 8
	v_mul_f32_e32 v3, v1, v3
	v_trunc_f32_e32 v3, v3
	v_fma_f32 v1, -v3, v2, v1
	v_cvt_i32_f32_e32 v3, v3
	s_lshl_b32 s33, s10, 10
	s_or_b32 s0, s0, 1
	v_cmp_ge_f32_e64 s[6:7], |v1|, v2
	s_and_b64 s[6:7], s[6:7], exec
	s_cselect_b32 s0, s0, 0
	v_readfirstlane_b32 s6, v3
	s_add_i32 s0, s6, s0
	s_mul_i32 s6, s0, s9
	s_sub_i32 s6, s11, s6
	s_sext_i32_i16 s6, s6
	s_add_i32 s22, s8, s6
	s_ashr_i32 s23, s22, 31
	s_bfe_i64 s[8:9], s[0:1], 0x100000
	s_lshl_b64 s[6:7], s[22:23], 19
	s_lshl_b64 s[8:9], s[8:9], 19
	s_add_u32 s68, s28, s8
	s_addc_u32 s69, s29, s9
	s_add_i32 s23, s33, 0
	s_add_i32 m0, s23, 0x10000
	v_mov_b32_e32 v133, 0
	global_load_lds_dwordx4 v132, s[68:69]
	s_add_i32 m0, s23, 0x12000
	s_add_u32 s8, s68, 0x40000
	global_load_lds_dwordx4 v136, s[68:69]
	s_addc_u32 s9, s69, 0
	s_add_i32 m0, s23, 0x14000
	v_mov_b32_e32 v137, v133
	global_load_lds_dwordx4 v132, s[8:9]
	s_add_i32 m0, s23, 0x16000
	s_add_u32 s66, s88, s6
	s_addc_u32 s67, s89, s7
	s_add_i32 s35, s23, 0x2000
	global_load_lds_dwordx4 v136, s[8:9]
	s_mov_b32 m0, s23
	s_add_u32 s6, s66, 0x40000
	global_load_lds_dwordx4 v130, s[66:67]
	s_mov_b32 m0, s35
	s_addc_u32 s7, s67, 0
	s_add_i32 s52, s23, 0x4000
	global_load_lds_dwordx4 v134, s[66:67]
	s_mov_b32 m0, s52
	s_add_i32 s53, s23, 0x6000
	global_load_lds_dwordx4 v130, s[6:7]
	s_mov_b32 m0, s53
	v_mov_b32_e32 v131, v133
	global_load_lds_dwordx4 v134, s[6:7]
	v_mov_b32_e32 v135, v133
	s_cmp_eq_u32 s1, 1
	s_mov_b32 s54, 0
	v_lshl_add_u64 v[8:9], s[68:69], 0, v[132:133]
	v_lshl_add_u64 v[6:7], s[68:69], 0, v[136:137]
	v_lshl_add_u64 v[2:3], s[66:67], 0, v[130:131]
	s_cselect_b64 s[6:7], -1, 0
	s_setprio 1
	s_cmp_lg_u32 s1, 1
	v_lshl_add_u64 v[4:5], s[66:67], 0, v[134:135]
	s_cbranch_scc1 .LBB0_823
	s_setprio 0
	s_barrier

.LBB0_901:
	s_add_u32 s10, s28, 0xb00000
	v_bfe_u32 v171, v1, 4, 2
	v_cndmask_b32_e64 v2, 0, 1, s[4:5]
	s_addc_u32 s11, s29, 0
	v_lshlrev_b32_e32 v168, 4, v1
	v_and_b32_e32 v169, 15, v1
	v_cmp_ne_u32_e64 s[0:1], 1, v2
	s_andn2_b64 vcc, exec, s[4:5]
	v_lshlrev_b32_e32 v170, 3, v171
	s_cbranch_vccnz .LBB0_1029
	v_lshrrev_b32_e32 v4, 1, v1
	v_lshrrev_b32_e32 v5, 5, v1
	v_and_b32_e32 v4, 24, v4
	v_and_b32_e32 v5, 4, v5
	v_bfe_u32 v6, v1, 2, 2
	v_and_b32_e32 v2, 32, v1
	v_bfe_u32 v3, v1, 2, 4
	v_or3_b32 v4, v5, v6, v4
	v_lshrrev_b32_e32 v5, 3, v1
	s_movk_i32 s3, 0x70
	v_bitop3_b32 v10, v168, v2, 48 bitop3:0x6c
	v_and_b32_e32 v11, 64, v1
	v_and_or_b32 v6, v5, s3, v3
	s_movk_i32 s3, 0x60
	v_or_b32_e32 v2, v10, v11
	v_and_or_b32 v5, v5, s3, v4
	v_lshrrev_b32_e32 v2, 1, v2
	v_mul_u32_u24_e32 v5, 0xb00, v5
	v_or_b32_e32 v5, v5, v2
	v_lshlrev_b32_e32 v142, 1, v5
	v_add_u32_e32 v5, 0x2000, v168
	v_lshrrev_b32_e32 v5, 7, v5
	s_movk_i32 s3, 0xf0
	s_lshr_b32 s4, s6, 6
	v_and_or_b32 v3, v5, s3, v3
	s_movk_i32 s3, 0xe0
	v_and_or_b32 v4, v5, s3, v4
	s_lshr_b32 s5, s6, 8
	s_lshl_b32 s3, s4, 10
	s_mul_i32 s9, s14, 0x160000
	v_mul_u32_u24_e32 v13, 0xb00, v3
	s_mul_hi_i32 s8, s14, 0x160000
	s_add_u32 s70, s10, s9
	v_or_b32_e32 v3, v13, v2
	s_addc_u32 s71, s11, s8
	s_add_i32 s33, s3, 0
	v_mul_u32_u24_e32 v12, 0xb00, v6
	v_lshlrev_b32_e32 v144, 1, v3
	v_mul_u32_u24_e32 v3, 0xb00, v4
	s_add_i32 m0, s33, 0x10000
	v_or_b32_e32 v6, v2, v12
	v_or_b32_e32 v2, v3, v2
	global_load_lds_dwordx4 v142, s[70:71]
	s_add_i32 m0, s33, 0x12000
	v_lshlrev_b32_e32 v146, 1, v2
	s_add_u32 s8, s70, 0xb0000
	global_load_lds_dwordx4 v146, s[70:71]
	s_addc_u32 s9, s71, 0
	s_add_i32 m0, s33, 0x14000
	s_mul_i32 s15, s52, 0x160000
	global_load_lds_dwordx4 v142, s[8:9]
	s_add_i32 m0, s33, 0x16000
	s_mul_hi_i32 s7, s52, 0x160000
	s_add_u32 s90, s64, s15
	s_addc_u32 s91, s65, s7
	s_add_i32 s35, s33, 0x2000
	v_lshlrev_b32_e32 v140, 1, v6
	global_load_lds_dwordx4 v146, s[8:9]
	s_mov_b32 m0, s33
	s_add_u32 s8, s90, 0xb0000
	global_load_lds_dwordx4 v140, s[90:91]
	s_mov_b32 m0, s35
	s_addc_u32 s9, s91, 0
	s_add_i32 s54, s33, 0x4000
	global_load_lds_dwordx4 v144, s[90:91]
	s_mov_b32 m0, s54
	s_add_i32 s55, s33, 0x6000
	global_load_lds_dwordx4 v140, s[8:9]
	s_mov_b32 m0, s55
	v_mov_b32_e32 v149, 0
	global_load_lds_dwordx4 v144, s[8:9]
	v_mov_b32_e32 v143, v149
	v_mov_b32_e32 v147, v149
	v_mov_b32_e32 v141, v149
	v_mov_b32_e32 v145, v149
	s_cmp_eq_u32 s5, 1
	s_mov_b32 s15, 0
	v_lshl_add_u64 v[8:9], s[70:71], 0, v[142:143]
	v_lshl_add_u64 v[6:7], s[70:71], 0, v[146:147]
	v_lshl_add_u64 v[2:3], s[90:91], 0, v[140:141]
	s_cselect_b64 s[16:17], -1, 0
	s_setprio 1
	s_cmp_lg_u32 s5, 1
	v_lshl_add_u64 v[4:5], s[90:91], 0, v[144:145]
	s_cbranch_scc1 .LBB0_904
	s_setprio 0
	s_barrier

.LBB0_1146:
	s_andn2_b64 vcc, exec, s[0:1]
	s_cbranch_vccnz .LBB0_1322
	s_waitcnt lgkmcnt(0)
	v_lshrrev_b32_e32 v3, 1, v10
	v_lshrrev_b32_e32 v4, 5, v10
	v_and_b32_e32 v3, 24, v3
	v_and_b32_e32 v4, 4, v4
	v_bfe_u32 v5, v10, 2, 2
	v_lshlrev_b32_e32 v1, 4, v10
	v_and_b32_e32 v2, 32, v10
	v_bfe_u32 v13, v10, 2, 4
	v_or3_b32 v3, v4, v5, v3
	v_lshrrev_b32_e32 v4, 3, v10
	s_movk_i32 s1, 0x70
	v_bitop3_b32 v11, v1, v2, 48 bitop3:0x6c
	v_and_b32_e32 v12, 64, v10
	v_and_or_b32 v5, v4, s1, v13
	s_movk_i32 s1, 0x60
	v_add_u32_e32 v14, 0x2000, v1
	s_add_u32 s3, s28, 0x1080000
	v_or_b32_e32 v2, v11, v12
	v_and_or_b32 v4, v4, s1, v3
	v_lshrrev_b32_e32 v1, 7, v14
	s_movk_i32 s1, 0xf0
	s_addc_u32 s33, s29, 0
	s_lshr_b32 s0, s6, 6
	v_lshl_or_b32 v148, v4, 11, v2
	v_and_or_b32 v4, v1, s1, v13
	s_movk_i32 s1, 0xe0
	s_ashr_i32 s95, s94, 31
	s_ashr_i32 s93, s92, 31
	v_and_or_b32 v1, v1, s1, v3
	s_lshr_b32 s1, s6, 8
	s_lshl_b32 s35, s0, 10
	s_lshl_b64 s[4:5], s[94:95], 19
	s_lshl_b64 s[8:9], s[92:93], 19
	s_add_u32 s96, s3, s8
	s_addc_u32 s97, s33, s9
	s_add_i32 s55, s35, 0
	s_add_i32 m0, s55, 0x10000
	v_lshl_or_b32 v152, v1, 11, v2
	global_load_lds_dwordx4 v148, s[96:97]
	s_add_i32 m0, s55, 0x12000
	s_add_u32 s8, s96, 0x40000
	global_load_lds_dwordx4 v152, s[96:97]
	s_addc_u32 s9, s97, 0
	s_add_i32 m0, s55, 0x14000
	v_lshl_or_b32 v146, v5, 11, v2
	global_load_lds_dwordx4 v148, s[8:9]
	s_add_i32 m0, s55, 0x16000
	v_lshl_or_b32 v150, v4, 11, v2
	global_load_lds_dwordx4 v152, s[8:9]
	s_add_u32 s8, s88, s4
	s_addc_u32 s9, s89, s5
	s_add_i32 s60, s55, 0x2000
	s_mov_b32 m0, s55
	s_add_u32 s4, s8, 0x40000
	global_load_lds_dwordx4 v146, s[8:9]
	s_mov_b32 m0, s60
	s_addc_u32 s5, s9, 0
	s_add_i32 s61, s55, 0x4000
	global_load_lds_dwordx4 v150, s[8:9]
	s_mov_b32 m0, s61
	s_add_i32 s86, s55, 0x6000
	global_load_lds_dwordx4 v146, s[4:5]
	s_mov_b32 m0, s86
	v_mov_b32_e32 v155, 0
	global_load_lds_dwordx4 v150, s[4:5]
	v_mov_b32_e32 v149, v155
	v_mov_b32_e32 v153, v155
	v_mov_b32_e32 v147, v155
	v_mov_b32_e32 v151, v155
	s_cmp_eq_u32 s1, 1
	s_mov_b32 s87, 0
	v_lshl_add_u64 v[8:9], s[96:97], 0, v[148:149]
	v_lshl_add_u64 v[6:7], s[96:97], 0, v[152:153]
	v_lshl_add_u64 v[2:3], s[8:9], 0, v[146:147]
	s_cselect_b64 s[38:39], -1, 0
	s_setprio 1
	s_cmp_lg_u32 s1, 1
	v_lshl_add_u64 v[4:5], s[8:9], 0, v[150:151]
	s_cbranch_scc1 .LBB0_1149
	s_setprio 0
	s_barrier

.LBB0_2639:
	s_andn2_b64 vcc, exec, s[0:1]
	s_cbranch_vccnz .LBB0_2711
	s_waitcnt lgkmcnt(0)
	v_lshrrev_b32_e32 v3, 1, v10
	v_lshrrev_b32_e32 v4, 5, v10
	v_and_b32_e32 v3, 24, v3
	v_and_b32_e32 v4, 4, v4
	v_bfe_u32 v5, v10, 2, 2
	v_lshlrev_b32_e32 v1, 4, v10
	v_and_b32_e32 v2, 32, v10
	v_bfe_u32 v13, v10, 2, 4
	v_or3_b32 v3, v4, v5, v3
	v_lshrrev_b32_e32 v4, 3, v10
	s_movk_i32 s1, 0x70
	v_bitop3_b32 v11, v1, v2, 48 bitop3:0x6c
	v_and_b32_e32 v12, 64, v10
	v_and_or_b32 v5, v4, s1, v13
	s_movk_i32 s1, 0x60
	v_add_u32_e32 v14, 0x2000, v1
	v_or_b32_e32 v2, v11, v12
	v_and_or_b32 v4, v4, s1, v3
	v_lshrrev_b32_e32 v1, 7, v14
	s_movk_i32 s1, 0xf0
	s_add_u32 s3, s28, 0x1700000
	v_lshl_or_b32 v132, v4, 11, v2
	v_and_or_b32 v4, v1, s1, v13
	s_movk_i32 s1, 0xe0
	s_addc_u32 s33, s29, 0
	v_and_or_b32 v1, v1, s1, v3
	s_lshr_b32 s1, s4, 6
	s_ashr_i32 s9, s8, 31
	s_ashr_i32 s7, s6, 31
	s_lshr_b32 s0, s4, 8
	s_lshl_b32 s35, s1, 10
	s_lshl_b64 s[12:13], s[8:9], 19
	s_lshl_b64 s[16:17], s[6:7], 19
	s_add_u32 s50, s3, s16
	s_addc_u32 s51, s33, s17
	s_add_i32 s54, s35, 0
	s_add_i32 m0, s54, 0x10000
	v_lshl_or_b32 v136, v1, 11, v2
	global_load_lds_dwordx4 v132, s[50:51]
	s_add_i32 m0, s54, 0x12000
	s_add_u32 s16, s50, 0x40000
	global_load_lds_dwordx4 v136, s[50:51]
	s_addc_u32 s17, s51, 0
	s_add_i32 m0, s54, 0x14000
	v_lshl_or_b32 v130, v5, 11, v2
	global_load_lds_dwordx4 v132, s[16:17]
	s_add_i32 m0, s54, 0x16000
	s_add_u32 s48, s88, s12
	s_addc_u32 s49, s89, s13
	s_add_i32 s55, s54, 0x2000
	global_load_lds_dwordx4 v136, s[16:17]
	s_mov_b32 m0, s54
	s_add_u32 s12, s48, 0x40000
	v_lshl_or_b32 v134, v4, 11, v2
	global_load_lds_dwordx4 v130, s[48:49]
	s_mov_b32 m0, s55
	s_addc_u32 s13, s49, 0
	s_add_i32 s56, s54, 0x4000
	global_load_lds_dwordx4 v134, s[48:49]
	s_mov_b32 m0, s56
	s_add_i32 s57, s54, 0x6000
	global_load_lds_dwordx4 v130, s[12:13]
	s_mov_b32 m0, s57
	v_mov_b32_e32 v139, 0
	global_load_lds_dwordx4 v134, s[12:13]
	v_mov_b32_e32 v133, v139
	v_mov_b32_e32 v137, v139
	v_mov_b32_e32 v131, v139
	v_mov_b32_e32 v135, v139
	s_cmp_eq_u32 s0, 1
	s_mov_b32 s58, 0
	v_lshl_add_u64 v[8:9], s[50:51], 0, v[132:133]
	v_lshl_add_u64 v[6:7], s[50:51], 0, v[136:137]
	v_lshl_add_u64 v[4:5], s[48:49], 0, v[130:131]
	v_lshl_add_u64 v[2:3], s[48:49], 0, v[134:135]
	s_cselect_b64 s[12:13], -1, 0
	s_setprio 1
	s_cmp_lg_u32 s0, 1
	s_movk_i32 s59, 0x4000
	s_cbranch_scc1 .LBB0_2642
	s_setprio 0
	s_barrier

.LBB0_2858:
	v_lshrrev_b32_e32 v4, 1, v168
	v_and_b32_e32 v13, 24, v4
	v_lshrrev_b32_e32 v4, 5, v168
	s_ashr_i32 s0, s9, 3
	v_and_b32_e32 v4, 4, v4
	v_bfe_u32 v5, v168, 2, 2
	v_lshlrev_b32_e32 v2, 4, v168
	s_waitcnt lgkmcnt(0)
	v_and_b32_e32 v3, 32, v168
	v_bfe_u32 v12, v168, 2, 4
	v_or3_b32 v4, v4, v5, v13
	v_lshrrev_b32_e32 v5, 3, v168
	s_movk_i32 s9, 0x70
	s_add_i32 s0, s8, s0
	v_bitop3_b32 v10, v2, v3, 48 bitop3:0x6c
	v_and_b32_e32 v11, 64, v168
	v_and_or_b32 v6, v5, s9, v12
	s_movk_i32 s9, 0x60
	v_add_u32_e32 v14, 0x2000, v2
	s_ashr_i32 s8, s0, 31
	v_or_b32_e32 v3, v10, v11
	v_and_or_b32 v5, v5, s9, v4
	v_lshrrev_b32_e32 v2, 7, v14
	s_movk_i32 s9, 0xf0
	s_lshr_b32 s8, s8, 27
	v_lshl_or_b32 v144, v5, 11, v3
	v_and_or_b32 v5, v2, s9, v12
	s_movk_i32 s9, 0xe0
	s_add_i32 s8, s0, s8
	v_and_or_b32 v2, v2, s9, v4
	s_ashr_i32 s9, s8, 5
	s_andn2_b32 s8, s8, 31
	s_sub_i32 s8, s0, s8
	s_bfe_i32 s0, s8, 0x80000
	s_bfe_u32 s0, s0, 0x3000c
	s_add_i32 s11, s8, s0
	s_bfe_i32 s0, s11, 0x80000
	s_and_b32 s11, s11, 0xf8
	s_sub_i32 s8, s8, s11
	s_lshl_b32 s9, s9, 3
	s_sext_i32_i16 s0, s0
	s_sext_i32_i8 s8, s8
	s_lshr_b32 s1, s12, 8
	s_lshr_b32 s0, s0, 3
	s_add_i32 s40, s9, s8
	s_lshr_b32 s10, s12, 6
	s_ashr_i32 s41, s40, 31
	s_bfe_i64 s[16:17], s[0:1], 0x100000
	s_lshl_b32 s33, s10, 10
	s_lshl_b64 s[8:9], s[40:41], 19
	s_lshl_b64 s[16:17], s[16:17], 19
	s_add_u32 s44, s4, s16
	s_addc_u32 s45, s5, s17
	s_add_i32 s35, s33, 0
	s_add_i32 m0, s35, 0x10000
	v_lshl_or_b32 v148, v2, 11, v3
	global_load_lds_dwordx4 v144, s[44:45]
	s_add_i32 m0, s35, 0x12000
	s_add_u32 s16, s44, 0x40000
	global_load_lds_dwordx4 v148, s[44:45]
	s_addc_u32 s17, s45, 0
	s_add_i32 m0, s35, 0x14000
	v_lshl_or_b32 v142, v6, 11, v3
	global_load_lds_dwordx4 v144, s[16:17]
	s_add_i32 m0, s35, 0x16000
	s_add_u32 s42, s20, s8
	s_addc_u32 s43, s21, s9
	s_add_i32 s41, s35, 0x2000
	global_load_lds_dwordx4 v148, s[16:17]
	s_mov_b32 m0, s35
	s_add_u32 s8, s42, 0x40000
	v_lshl_or_b32 v146, v5, 11, v3
	global_load_lds_dwordx4 v142, s[42:43]
	s_mov_b32 m0, s41
	s_addc_u32 s9, s43, 0
	s_add_i32 s48, s35, 0x4000
	global_load_lds_dwordx4 v146, s[42:43]
	s_mov_b32 m0, s48
	s_add_i32 s49, s35, 0x6000
	global_load_lds_dwordx4 v142, s[8:9]
	s_mov_b32 m0, s49
	v_mov_b32_e32 v145, 0
	global_load_lds_dwordx4 v146, s[8:9]
	v_mov_b32_e32 v149, v145
	v_mov_b32_e32 v143, v145
	v_mov_b32_e32 v147, v145
	s_cmp_eq_u32 s1, 1
	s_mov_b32 s50, 0
	v_lshl_add_u64 v[8:9], s[44:45], 0, v[144:145]
	v_lshl_add_u64 v[6:7], s[44:45], 0, v[148:149]
	v_lshl_add_u64 v[2:3], s[42:43], 0, v[142:143]
	s_cselect_b64 s[8:9], -1, 0
	s_setprio 1
	s_cmp_lg_u32 s1, 1
	v_lshl_add_u64 v[4:5], s[42:43], 0, v[146:147]
	s_cbranch_scc1 .LBB0_2860
	s_setprio 0
	s_barrier

.LBB0_2904:
	v_lshrrev_b32_e32 v4, 1, v161
	v_lshrrev_b32_e32 v5, 5, v161
	s_ashr_i32 s0, s5, 3
	v_and_b32_e32 v4, 24, v4
	v_and_b32_e32 v5, 4, v5
	v_bfe_u32 v6, v161, 2, 2
	v_lshlrev_b32_e32 v2, 4, v161
	s_waitcnt lgkmcnt(0)
	v_and_b32_e32 v3, 32, v161
	v_bfe_u32 v12, v161, 2, 4
	v_or3_b32 v4, v5, v6, v4
	v_lshrrev_b32_e32 v5, 3, v161
	s_movk_i32 s5, 0x70
	s_add_i32 s0, s4, s0
	v_bitop3_b32 v10, v2, v3, 48 bitop3:0x6c
	v_and_b32_e32 v11, 64, v161
	v_and_or_b32 v6, v5, s5, v12
	s_movk_i32 s5, 0x60
	v_add_u32_e32 v13, 0x2000, v2
	s_ashr_i32 s4, s0, 31
	v_or_b32_e32 v3, v10, v11
	v_and_or_b32 v5, v5, s5, v4
	v_lshrrev_b32_e32 v2, 7, v13
	s_movk_i32 s5, 0xf0
	s_lshr_b32 s4, s4, 26
	v_lshl_or_b32 v132, v5, 11, v3
	v_and_or_b32 v5, v2, s5, v12
	s_movk_i32 s5, 0xe0
	s_add_i32 s4, s0, s4
	v_and_or_b32 v2, v2, s5, v4
	s_ashr_i32 s5, s4, 6
	s_andn2_b32 s4, s4, 63
	s_sub_i32 s4, s0, s4
	s_bfe_i32 s0, s4, 0x80000
	s_bfe_u32 s0, s0, 0x3000c
	s_add_i32 s8, s4, s0
	s_bfe_i32 s0, s8, 0x80000
	s_and_b32 s8, s8, 0xf8
	s_sub_i32 s4, s4, s8
	s_lshl_b32 s5, s5, 3
	s_sext_i32_i16 s0, s0
	s_sext_i32_i8 s4, s4
	s_lshr_b32 s1, s16, 8
	s_lshr_b32 s0, s0, 3
	s_add_i32 s4, s5, s4
	s_lshr_b32 s10, s16, 6
	s_ashr_i32 s5, s4, 31
	s_bfe_i64 s[18:19], s[0:1], 0x100000
	s_lshl_b32 s21, s10, 10
	s_lshl_b64 s[8:9], s[4:5], 19
	s_lshl_b64 s[18:19], s[18:19], 19
	s_add_u32 s46, s6, s18
	s_addc_u32 s47, s7, s19
	s_add_i32 s33, s21, 0
	s_add_i32 m0, s33, 0x10000
	v_lshl_or_b32 v136, v2, 11, v3
	global_load_lds_dwordx4 v132, s[46:47]
	s_add_i32 m0, s33, 0x12000
	s_add_u32 s18, s46, 0x40000
	global_load_lds_dwordx4 v136, s[46:47]
	s_addc_u32 s19, s47, 0
	s_add_i32 m0, s33, 0x14000
	v_lshl_or_b32 v130, v6, 11, v3
	global_load_lds_dwordx4 v132, s[18:19]
	s_add_i32 m0, s33, 0x16000
	s_add_u32 s44, s88, s8
	s_addc_u32 s45, s89, s9
	s_add_i32 s35, s33, 0x2000
	global_load_lds_dwordx4 v136, s[18:19]
	s_mov_b32 m0, s33
	s_add_u32 s8, s44, 0x40000
	v_lshl_or_b32 v134, v5, 11, v3
	global_load_lds_dwordx4 v130, s[44:45]
	s_mov_b32 m0, s35
	s_addc_u32 s9, s45, 0
	s_add_i32 s50, s33, 0x4000
	global_load_lds_dwordx4 v134, s[44:45]
	s_mov_b32 m0, s50
	s_add_i32 s51, s33, 0x6000
	global_load_lds_dwordx4 v130, s[8:9]
	s_mov_b32 m0, s51
	v_mov_b32_e32 v133, 0
	global_load_lds_dwordx4 v134, s[8:9]
	v_mov_b32_e32 v137, v133
	v_mov_b32_e32 v131, v133
	v_mov_b32_e32 v135, v133
	s_cmp_eq_u32 s1, 1
	s_mov_b32 s52, 0
	v_lshl_add_u64 v[8:9], s[46:47], 0, v[132:133]
	v_lshl_add_u64 v[6:7], s[46:47], 0, v[136:137]
	v_lshl_add_u64 v[2:3], s[44:45], 0, v[130:131]
	s_cselect_b64 s[8:9], -1, 0
	s_setprio 1
	s_cmp_lg_u32 s1, 1
	v_lshl_add_u64 v[4:5], s[44:45], 0, v[134:135]
	s_cbranch_scc1 .LBB0_2906
	s_setprio 0
	s_barrier

.LBB0_3017:
	v_lshrrev_b32_e32 v4, 1, v164
	v_and_b32_e32 v13, 24, v4
	v_lshrrev_b32_e32 v4, 5, v164
	s_ashr_i32 s0, s11, 3
	v_and_b32_e32 v4, 4, v4
	v_bfe_u32 v5, v164, 2, 2
	v_lshlrev_b32_e32 v2, 4, v164
	s_waitcnt lgkmcnt(0)
	v_and_b32_e32 v3, 32, v164
	v_bfe_u32 v12, v164, 2, 4
	v_or3_b32 v4, v4, v5, v13
	v_lshrrev_b32_e32 v5, 3, v164
	s_movk_i32 s11, 0x70
	s_add_i32 s0, s10, s0
	v_bitop3_b32 v10, v2, v3, 48 bitop3:0x6c
	v_and_b32_e32 v11, 64, v164
	v_and_or_b32 v6, v5, s11, v12
	s_movk_i32 s11, 0x60
	v_add_u32_e32 v14, 0x2000, v2
	s_ashr_i32 s10, s0, 31
	v_or_b32_e32 v3, v10, v11
	v_and_or_b32 v5, v5, s11, v4
	v_lshrrev_b32_e32 v2, 7, v14
	s_movk_i32 s11, 0xf0
	s_lshr_b32 s10, s10, 27
	v_lshl_or_b32 v140, v5, 11, v3
	v_and_or_b32 v5, v2, s11, v12
	s_movk_i32 s11, 0xe0
	s_add_i32 s10, s0, s10
	v_and_or_b32 v2, v2, s11, v4
	s_ashr_i32 s11, s10, 5
	s_andn2_b32 s10, s10, 31
	s_sub_i32 s10, s0, s10
	s_bfe_i32 s0, s10, 0x80000
	s_bfe_u32 s0, s0, 0x3000c
	s_add_i32 s13, s10, s0
	s_bfe_i32 s0, s13, 0x80000
	s_and_b32 s13, s13, 0xf8
	s_sub_i32 s10, s10, s13
	s_lshl_b32 s11, s11, 3
	s_sext_i32_i16 s0, s0
	s_sext_i32_i8 s10, s10
	s_lshr_b32 s1, s16, 8
	s_lshr_b32 s0, s0, 3
	s_add_i32 s38, s11, s10
	s_lshr_b32 s12, s16, 6
	s_ashr_i32 s39, s38, 31
	s_bfe_i64 s[18:19], s[0:1], 0x100000
	s_lshl_b32 s33, s12, 10
	s_lshl_b64 s[10:11], s[38:39], 19
	s_lshl_b64 s[18:19], s[18:19], 19
	s_add_u32 s42, s4, s18
	s_addc_u32 s43, s5, s19
	s_add_i32 s35, s33, 0
	s_add_i32 m0, s35, 0x10000
	v_lshl_or_b32 v144, v2, 11, v3
	global_load_lds_dwordx4 v140, s[42:43]
	s_add_i32 m0, s35, 0x12000
	s_add_u32 s18, s42, 0x40000
	global_load_lds_dwordx4 v144, s[42:43]
	s_addc_u32 s19, s43, 0
	s_add_i32 m0, s35, 0x14000
	v_lshl_or_b32 v138, v6, 11, v3
	global_load_lds_dwordx4 v140, s[18:19]
	s_add_i32 m0, s35, 0x16000
	s_add_u32 s40, s14, s10
	s_addc_u32 s41, s15, s11
	s_add_i32 s39, s35, 0x2000
	global_load_lds_dwordx4 v144, s[18:19]
	s_mov_b32 m0, s35
	s_add_u32 s10, s40, 0x40000
	v_lshl_or_b32 v142, v5, 11, v3
	global_load_lds_dwordx4 v138, s[40:41]
	s_mov_b32 m0, s39
	s_addc_u32 s11, s41, 0
	s_add_i32 s46, s35, 0x4000
	global_load_lds_dwordx4 v142, s[40:41]
	s_mov_b32 m0, s46
	s_add_i32 s47, s35, 0x6000
	global_load_lds_dwordx4 v138, s[10:11]
	s_mov_b32 m0, s47
	v_mov_b32_e32 v141, 0
	global_load_lds_dwordx4 v142, s[10:11]
	v_mov_b32_e32 v145, v141
	v_mov_b32_e32 v139, v141
	v_mov_b32_e32 v143, v141
	s_cmp_eq_u32 s1, 1
	s_mov_b32 s48, 0
	v_lshl_add_u64 v[8:9], s[42:43], 0, v[140:141]
	v_lshl_add_u64 v[6:7], s[42:43], 0, v[144:145]
	v_lshl_add_u64 v[2:3], s[40:41], 0, v[138:139]
	s_cselect_b64 s[10:11], -1, 0
	s_setprio 1
	s_cmp_lg_u32 s1, 1
	v_lshl_add_u64 v[4:5], s[40:41], 0, v[142:143]
	s_cbranch_scc1 .LBB0_3019
	s_setprio 0
	s_barrier

.LBB0_3118:
	s_add_u32 s8, s28, 0x2700000
	v_bfe_u32 v165, v1, 4, 2
	v_cndmask_b32_e64 v2, 0, 1, s[4:5]
	s_addc_u32 s9, s29, 0
	v_lshlrev_b32_e32 v162, 4, v1
	v_and_b32_e32 v164, 15, v1
	v_cmp_ne_u32_e64 s[0:1], 1, v2
	s_andn2_b64 vcc, exec, s[4:5]
	v_lshlrev_b32_e32 v163, 3, v165
	s_cbranch_vccnz .LBB0_3186
	s_waitcnt lgkmcnt(0)
	v_lshrrev_b32_e32 v3, 1, v1
	v_lshrrev_b32_e32 v4, 5, v1
	v_and_b32_e32 v3, 24, v3
	v_and_b32_e32 v4, 4, v4
	v_bfe_u32 v5, v1, 2, 2
	v_and_b32_e32 v2, 32, v1
	v_bfe_u32 v12, v1, 2, 4
	v_or3_b32 v3, v4, v5, v3
	v_lshrrev_b32_e32 v4, 3, v1
	s_movk_i32 s3, 0x70
	v_bitop3_b32 v10, v162, v2, 48 bitop3:0x6c
	v_and_b32_e32 v11, 64, v1
	v_and_or_b32 v5, v4, s3, v12
	s_movk_i32 s3, 0x60
	v_or_b32_e32 v2, v10, v11
	v_and_or_b32 v4, v4, s3, v3
	v_add_u32_e32 v13, 0x2000, v162
	v_lshl_or_b32 v142, v4, 11, v2
	v_lshrrev_b32_e32 v4, 7, v13
	s_movk_i32 s3, 0xf0
	s_lshr_b32 s4, s6, 6
	v_lshl_or_b32 v140, v5, 11, v2
	v_and_or_b32 v5, v4, s3, v12
	s_movk_i32 s3, 0xe0
	s_ashr_i32 s43, s42, 31
	s_ashr_i32 s11, s10, 31
	v_and_or_b32 v3, v4, s3, v3
	s_lshr_b32 s5, s6, 8
	s_lshl_b32 s3, s4, 10
	s_lshl_b64 s[16:17], s[42:43], 19
	s_lshl_b64 s[18:19], s[10:11], 19
	s_add_u32 s46, s8, s18
	s_addc_u32 s47, s9, s19
	s_add_i32 s33, s3, 0
	s_add_i32 m0, s33, 0x10000
	v_lshl_or_b32 v146, v3, 11, v2
	global_load_lds_dwordx4 v142, s[46:47]
	s_add_i32 m0, s33, 0x12000
	s_add_u32 s18, s46, 0x40000
	global_load_lds_dwordx4 v146, s[46:47]
	s_addc_u32 s19, s47, 0
	s_add_i32 m0, s33, 0x14000
	v_lshl_or_b32 v144, v5, 11, v2
	global_load_lds_dwordx4 v142, s[18:19]
	s_add_i32 m0, s33, 0x16000
	s_add_u32 s44, s62, s16
	s_addc_u32 s45, s63, s17
	s_add_i32 s35, s33, 0x2000
	global_load_lds_dwordx4 v146, s[18:19]
	s_mov_b32 m0, s33
	s_add_u32 s16, s44, 0x40000
	global_load_lds_dwordx4 v140, s[44:45]
	s_mov_b32 m0, s35
	s_addc_u32 s17, s45, 0
	s_add_i32 s50, s33, 0x4000
	global_load_lds_dwordx4 v144, s[44:45]
	s_mov_b32 m0, s50
	s_add_i32 s51, s33, 0x6000
	global_load_lds_dwordx4 v140, s[16:17]
	s_mov_b32 m0, s51
	v_mov_b32_e32 v143, 0
	global_load_lds_dwordx4 v144, s[16:17]
	v_mov_b32_e32 v147, v143
	v_mov_b32_e32 v141, v143
	v_mov_b32_e32 v145, v143
	s_cmp_eq_u32 s5, 1
	s_mov_b32 s11, 0
	v_lshl_add_u64 v[8:9], s[46:47], 0, v[142:143]
	v_lshl_add_u64 v[6:7], s[46:47], 0, v[146:147]
	v_lshl_add_u64 v[2:3], s[44:45], 0, v[140:141]
	s_cselect_b64 s[16:17], -1, 0
	s_setprio 1
	s_cmp_lg_u32 s5, 1
	v_lshl_add_u64 v[4:5], s[44:45], 0, v[144:145]
	s_cbranch_scc1 .LBB0_3121
	s_setprio 0
	s_barrier

.LBB0_3281:
	s_waitcnt lgkmcnt(0)
	v_lshrrev_b32_e32 v3, 1, v10
	v_lshrrev_b32_e32 v4, 5, v10
	v_and_b32_e32 v3, 24, v3
	v_and_b32_e32 v4, 4, v4
	v_bfe_u32 v5, v10, 2, 2
	s_ashr_i32 s0, s5, 3
	v_lshlrev_b32_e32 v1, 4, v10
	v_and_b32_e32 v2, 32, v10
	v_bfe_u32 v13, v10, 2, 4
	v_or3_b32 v3, v4, v5, v3
	v_lshrrev_b32_e32 v4, 3, v10
	s_movk_i32 s5, 0x70
	s_add_u32 s33, s28, 0x2900000
	v_bitop3_b32 v11, v1, v2, 48 bitop3:0x6c
	v_and_b32_e32 v12, 64, v10
	v_and_or_b32 v5, v4, s5, v13
	s_movk_i32 s5, 0x60
	v_add_u32_e32 v14, 0x2000, v1
	s_addc_u32 s35, s29, 0
	v_or_b32_e32 v2, v11, v12
	v_and_or_b32 v4, v4, s5, v3
	v_lshrrev_b32_e32 v1, 7, v14
	s_movk_i32 s5, 0xf0
	s_add_i32 s0, s4, s0
	v_lshl_or_b32 v132, v4, 11, v2
	v_and_or_b32 v4, v1, s5, v13
	s_movk_i32 s5, 0xe0
	s_mul_hi_i32 s4, s0, 0x2e8ba2e9
	v_and_or_b32 v1, v1, s5, v3
	s_lshr_b32 s5, s4, 31
	s_ashr_i32 s4, s4, 5
	s_add_i32 s4, s4, s5
	s_lshl_b32 s8, s4, 3
	s_sub_i32 s5, 0x45, s8
	s_mulk_i32 s4, 0xb0
	s_min_u32 s9, s5, 8
	s_sub_i32 s11, s0, s4
	v_lshl_or_b32 v130, v5, 11, v2
	v_lshl_or_b32 v134, v4, 11, v2
	v_lshl_or_b32 v136, v1, 11, v2
	s_sext_i32_i16 s0, s11
	v_cvt_f32_ubyte0_e32 v2, s9
	v_cvt_f32_i32_e32 v1, s0
	v_rcp_iflag_f32_e32 v3, v2
	s_lshr_b32 s10, s14, 6
	s_ashr_i32 s0, s0, 30
	s_lshr_b32 s1, s14, 8
	v_mul_f32_e32 v3, v1, v3
	v_trunc_f32_e32 v3, v3
	v_fma_f32 v1, -v3, v2, v1
	v_cvt_i32_f32_e32 v3, v3
	s_lshl_b32 s40, s10, 10
	s_or_b32 s0, s0, 1
	v_cmp_ge_f32_e64 s[4:5], |v1|, v2
	s_and_b64 s[4:5], s[4:5], exec
	s_cselect_b32 s0, s0, 0
	v_readfirstlane_b32 s4, v3
	s_add_i32 s0, s4, s0
	s_mul_i32 s4, s0, s9
	s_sub_i32 s4, s11, s4
	s_sext_i32_i16 s4, s4
	s_add_i32 s4, s8, s4
	s_ashr_i32 s5, s4, 31
	s_bfe_i64 s[16:17], s[0:1], 0x100000
	s_lshl_b64 s[8:9], s[4:5], 19
	s_lshl_b64 s[16:17], s[16:17], 19
	s_add_u32 s36, s33, s16
	s_addc_u32 s37, s35, s17
	s_add_i32 s41, s40, 0
	s_add_i32 m0, s41, 0x10000
	v_mov_b32_e32 v133, 0
	global_load_lds_dwordx4 v132, s[36:37]
	s_add_i32 m0, s41, 0x12000
	s_add_u32 s16, s36, 0x40000
	global_load_lds_dwordx4 v136, s[36:37]
	s_addc_u32 s17, s37, 0
	s_add_i32 m0, s41, 0x14000
	v_mov_b32_e32 v137, v133
	global_load_lds_dwordx4 v132, s[16:17]
	s_add_i32 m0, s41, 0x16000
	s_add_u32 s22, s88, s8
	s_addc_u32 s23, s89, s9
	s_add_i32 s42, s41, 0x2000
	global_load_lds_dwordx4 v136, s[16:17]
	s_mov_b32 m0, s41
	s_add_u32 s8, s22, 0x40000
	global_load_lds_dwordx4 v130, s[22:23]
	s_mov_b32 m0, s42
	s_addc_u32 s9, s23, 0
	s_add_i32 s43, s41, 0x4000
	global_load_lds_dwordx4 v134, s[22:23]
	s_mov_b32 m0, s43
	s_add_i32 s44, s41, 0x6000
	global_load_lds_dwordx4 v130, s[8:9]
	s_mov_b32 m0, s44
	v_mov_b32_e32 v131, v133
	global_load_lds_dwordx4 v134, s[8:9]
	v_mov_b32_e32 v135, v133
	s_cmp_eq_u32 s1, 1
	s_mov_b32 s45, 0
	v_lshl_add_u64 v[8:9], s[36:37], 0, v[132:133]
	v_lshl_add_u64 v[6:7], s[36:37], 0, v[136:137]
	v_lshl_add_u64 v[2:3], s[22:23], 0, v[130:131]
	s_cselect_b64 s[8:9], -1, 0
	s_setprio 1
	s_cmp_lg_u32 s1, 1
	v_lshl_add_u64 v[4:5], s[22:23], 0, v[134:135]
	s_cbranch_scc1 .LBB0_3283
	s_setprio 0
	s_barrier

.LBB0_3362:
	s_andn2_b64 vcc, exec, s[0:1]
	s_cbranch_vccnz .LBB0_3434
	v_lshrrev_b32_e32 v4, 1, v140
	v_lshrrev_b32_e32 v5, 5, v140
	v_and_b32_e32 v4, 24, v4
	v_and_b32_e32 v5, 4, v5
	v_bfe_u32 v6, v140, 2, 2
	v_lshlrev_b32_e32 v1, 4, v140
	v_and_b32_e32 v2, 32, v140
	s_waitcnt lgkmcnt(0)
	v_bfe_u32 v3, v140, 2, 4
	v_or3_b32 v4, v5, v6, v4
	v_lshrrev_b32_e32 v5, 3, v140
	s_movk_i32 s1, 0x70
	v_bitop3_b32 v10, v1, v2, 48 bitop3:0x6c
	v_and_or_b32 v6, v5, s1, v3
	s_movk_i32 s1, 0x60
	v_add_u32_e32 v1, 0x2000, v1
	v_and_or_b32 v5, v5, s1, v4
	v_lshrrev_b32_e32 v1, 7, v1
	s_movk_i32 s1, 0xf0
	s_lshr_b32 s0, s6, 6
	v_and_b32_e32 v11, 64, v140
	v_and_or_b32 v3, v1, s1, v3
	s_movk_i32 s1, 0xe0
	v_or_b32_e32 v2, v10, v11
	v_and_or_b32 v1, v1, s1, v4
	s_lshr_b32 s1, s6, 8
	s_lshl_b32 s3, s0, 10
	s_mul_i32 s5, s10, 0x160000
	v_lshrrev_b32_e32 v2, 1, v2
	v_mul_u32_u24_e32 v5, 0xb00, v5
	s_mul_hi_i32 s4, s10, 0x160000
	s_add_u32 s40, s12, s5
	v_or_b32_e32 v5, v5, v2
	s_addc_u32 s41, s13, s4
	s_add_i32 s33, s3, 0
	v_lshlrev_b32_e32 v144, 1, v5
	v_mul_u32_u24_e32 v1, 0xb00, v1
	s_add_i32 m0, s33, 0x10000
	v_or_b32_e32 v1, v1, v2
	global_load_lds_dwordx4 v144, s[40:41]
	s_add_i32 m0, s33, 0x12000
	v_lshlrev_b32_e32 v148, 1, v1
	s_add_u32 s4, s40, 0xb0000
	global_load_lds_dwordx4 v148, s[40:41]
	s_addc_u32 s5, s41, 0
	s_add_i32 m0, s33, 0x14000
	s_mul_i32 s11, s60, 0x160000
	global_load_lds_dwordx4 v144, s[4:5]
	s_add_i32 m0, s33, 0x16000
	v_mul_u32_u24_e32 v12, 0xb00, v6
	s_mul_hi_i32 s7, s60, 0x160000
	s_add_u32 s38, s64, s11
	v_or_b32_e32 v6, v2, v12
	v_mul_u32_u24_e32 v13, 0xb00, v3
	s_addc_u32 s39, s65, s7
	s_add_i32 s35, s33, 0x2000
	v_lshlrev_b32_e32 v142, 1, v6
	v_or_b32_e32 v3, v13, v2
	global_load_lds_dwordx4 v148, s[4:5]
	s_mov_b32 m0, s33
	s_add_u32 s4, s38, 0xb0000
	v_lshlrev_b32_e32 v146, 1, v3
	global_load_lds_dwordx4 v142, s[38:39]
	s_mov_b32 m0, s35
	s_addc_u32 s5, s39, 0
	s_add_i32 s44, s33, 0x4000
	global_load_lds_dwordx4 v146, s[38:39]
	s_mov_b32 m0, s44
	s_add_i32 s45, s33, 0x6000
	global_load_lds_dwordx4 v142, s[4:5]
	s_mov_b32 m0, s45
	v_mov_b32_e32 v145, 0
	global_load_lds_dwordx4 v146, s[4:5]
	v_mov_b32_e32 v149, v145
	v_mov_b32_e32 v143, v145
	v_mov_b32_e32 v147, v145
	s_cmp_eq_u32 s1, 1
	s_mov_b32 s11, 0
	v_lshl_add_u64 v[8:9], s[40:41], 0, v[144:145]
	v_lshl_add_u64 v[6:7], s[40:41], 0, v[148:149]
	v_lshl_add_u64 v[2:3], s[38:39], 0, v[142:143]
	s_cselect_b64 s[14:15], -1, 0
	s_setprio 1
	s_cmp_lg_u32 s1, 1
	v_lshl_add_u64 v[4:5], s[38:39], 0, v[146:147]
	s_cbranch_scc1 .LBB0_3365
	s_setprio 0
	s_barrier

.LBB0_3441:
	s_ashr_i32 s6, s6, 3
	s_add_i32 s5, s5, s6
	s_ashr_i32 s6, s5, 31
	s_lshr_b32 s6, s6, 27
	s_waitcnt lgkmcnt(0)
	v_lshrrev_b32_e32 v3, 1, v140
	v_lshrrev_b32_e32 v4, 5, v140
	s_add_i32 s6, s5, s6
	v_and_b32_e32 v3, 24, v3
	v_and_b32_e32 v4, 4, v4
	v_bfe_u32 v5, v140, 2, 2
	s_ashr_i32 s7, s6, 5
	s_andn2_b32 s6, s6, 31
	v_lshlrev_b32_e32 v152, 4, v140
	v_and_b32_e32 v1, 32, v140
	v_bfe_u32 v2, v140, 2, 4
	v_or3_b32 v3, v4, v5, v3
	v_lshrrev_b32_e32 v4, 3, v140
	s_movk_i32 s0, 0x70
	s_sub_i32 s6, s5, s6
	v_bitop3_b32 v10, v152, v1, 48 bitop3:0x6c
	v_and_b32_e32 v11, 64, v140
	v_and_or_b32 v5, v4, s0, v2
	s_movk_i32 s0, 0x60
	s_bfe_i32 s5, s6, 0x80000
	v_or_b32_e32 v1, v10, v11
	v_and_or_b32 v4, v4, s0, v3
	s_bfe_u32 s5, s5, 0x3000c
	v_lshrrev_b32_e32 v1, 1, v1
	v_mul_u32_u24_e32 v4, 0xb00, v4
	s_add_i32 s10, s6, s5
	v_or_b32_e32 v4, v4, v1
	s_bfe_i32 s5, s10, 0x80000
	s_and_b32 s10, s10, 0xf8
	v_lshlrev_b32_e32 v132, 1, v4
	v_add_u32_e32 v4, 0x2000, v152
	s_sub_i32 s6, s6, s10
	v_lshrrev_b32_e32 v4, 7, v4
	s_movk_i32 s0, 0xf0
	s_lshl_b32 s7, s7, 3
	s_sext_i32_i16 s11, s5
	s_sext_i32_i8 s6, s6
	s_lshr_b32 s1, s4, 6
	v_and_or_b32 v2, v4, s0, v2
	s_movk_i32 s0, 0xe0
	s_add_i32 s10, s7, s6
	s_ashr_i32 s6, s11, 3
	v_and_or_b32 v3, v4, s0, v3
	s_lshr_b32 s0, s4, 8
	s_lshl_b32 s33, s1, 10
	s_lshr_b32 s5, s11, 3
	s_mul_hi_i32 s7, s6, 0x160000
	s_mul_i32 s6, s6, 0x160000
	v_mul_u32_u24_e32 v13, 0xb00, v2
	s_add_u32 s42, s12, s6
	v_or_b32_e32 v2, v13, v1
	s_addc_u32 s43, s13, s7
	s_add_i32 s35, s33, 0
	v_mul_u32_u24_e32 v12, 0xb00, v5
	v_lshlrev_b32_e32 v134, 1, v2
	v_mul_u32_u24_e32 v2, 0xb00, v3
	s_add_i32 m0, s35, 0x10000
	v_or_b32_e32 v5, v1, v12
	v_or_b32_e32 v1, v2, v1
	global_load_lds_dwordx4 v132, s[42:43]
	s_add_i32 m0, s35, 0x12000
	v_lshlrev_b32_e32 v136, 1, v1
	s_add_u32 s6, s42, 0xb0000
	global_load_lds_dwordx4 v136, s[42:43]
	s_addc_u32 s7, s43, 0
	s_add_i32 m0, s35, 0x14000
	s_mul_i32 s15, s10, 0x160000
	global_load_lds_dwordx4 v132, s[6:7]
	s_add_i32 m0, s35, 0x16000
	s_mul_hi_i32 s14, s10, 0x160000
	s_add_u32 s40, s64, s15
	s_addc_u32 s41, s65, s14
	s_add_i32 s48, s35, 0x2000
	v_lshlrev_b32_e32 v130, 1, v5
	global_load_lds_dwordx4 v136, s[6:7]
	s_mov_b32 m0, s35
	s_add_u32 s6, s40, 0xb0000
	global_load_lds_dwordx4 v130, s[40:41]
	s_mov_b32 m0, s48
	s_addc_u32 s7, s41, 0
	s_add_i32 s49, s35, 0x4000
	global_load_lds_dwordx4 v134, s[40:41]
	s_mov_b32 m0, s49
	s_add_i32 s50, s35, 0x6000
	global_load_lds_dwordx4 v130, s[6:7]
	s_mov_b32 m0, s50
	v_mov_b32_e32 v133, 0
	global_load_lds_dwordx4 v134, s[6:7]
	v_mov_b32_e32 v137, v133
	v_mov_b32_e32 v131, v133
	v_mov_b32_e32 v135, v133
	s_cmp_eq_u32 s0, 1
	v_lshl_add_u64 v[8:9], s[42:43], 0, v[132:133]
	v_lshl_add_u64 v[6:7], s[42:43], 0, v[136:137]
	v_lshl_add_u64 v[2:3], s[40:41], 0, v[130:131]
	s_cselect_b64 s[14:15], -1, 0
	s_setprio 1
	s_cmp_lg_u32 s0, 1
	v_lshl_add_u64 v[4:5], s[40:41], 0, v[134:135]
	s_cbranch_scc1 .LBB0_3443
	s_setprio 0
	s_barrier
